# previous stack plus the same LDS-DMA 4/4 rebalance and MFMA hoist applied to the merge GEMM K-loop
# baseline (speedup 1.0000x reference)
; #define PG8_STAGE(bufoff, gbase, voff) do { _Pragma("unroll") for (int _i = 0; _i < 2; ++_i) \
;         __builtin_amdgcn_global_load_lds((const unsigned*)((const char*)(gbase) + (voff)[_i]), (PG8_LAS unsigned*)(lds + (bufoff) + ldsw + _i * 8192), 16, 0, 0); } while (0)
; #define PG8_WAIT_V(n) asm volatile("s_waitcnt vmcnt(" #n ")" ::: "memory")
; #define PG8_BAR __builtin_amdgcn_s_barrier()
; template <class Epi, class Sched, bool ALIGN_EPI = false>
; __device__ __forceinline__ void gemm_phase(PG8_LAS unsigned char* lds, const Gemm g, const Sched& S, const Epi& E, int tid_in) {
;     ...
;     const int aoff = lds_byte(wr * 64 + fr, fq * 8), boff = lds_byte(wc * 32 + fr, fq * 8);
;     ...
;     PG8_STAGE(PG8_SB(0, 0), cB, voffB); PG8_STAGE(PG8_SB(0, 1), cB + hstepB, voffB); PG8_STAGE(PG8_SA(0, 0), cA, voffA); PG8_STAGE(PG8_SA(0, 1), cA + hstepA, voffA);
;     if (wr == 1) PG8_BAR;
;     PG8_WAIT_V(2); PG8_BAR;
;     PG8_STAGE(PG8_SB(1, 0), cB + kstep, voffB); PG8_STAGE(PG8_SA(1, 0), cA + kstep, voffA); PG8_STAGE(PG8_SB(1, 1), cB + hstepB + kstep, voffB);
;     PG8_WAIT_V(6); PG8_BAR;
.LBB0_139:
	s_waitcnt vmcnt(0)
	v_bfe_u32 v17, v190, 4, 2
	v_and_b32_e32 v16, 15, v190
	s_lshl_b32 s38, s4, 6
	v_lshlrev_b32_e32 v18, 3, v17
	v_lshlrev_b32_e32 v17, 4, v17
	s_lshl_b32 s3, s3, 5
	v_or_b32_e32 v191, s38, v16
	v_lshl_or_b32 v16, v16, 6, v17
	v_lshlrev_b32_e32 v17, 2, v190
	s_and_b32 s39, s3, 0x60
	s_add_i32 m0, s34, 0x18000
	v_lshl_add_u64 v[6:7], v[6:7], 0, s[96:97]
	s_lshl_b32 s4, s4, 13
	v_and_b32_e32 v17, 32, v17
	s_lshl_b32 s3, s39, 7
	s_waitcnt vmcnt(2)
	s_barrier
	global_load_lds_dwordx4 v[6:7], off
	v_lshl_add_u64 v[4:5], v[4:5], 0, s[96:97]
	s_add_i32 m0, s34, 0x1a000
	s_add_i32 s40, s34, 0x8000
	s_add_i32 s41, s34, 0xa000
	v_bitop3_b32 v19, v16, s4, v17 bitop3:0xde
	global_load_lds_dwordx4 v[4:5], off
	s_add_u32 s4, s18, 0x40080
	s_addc_u32 s5, s19, 0
	s_add_i32 m0, s34, 0x1c000
	v_lshl_add_u64 v[0:1], s[4:5], 0, v[176:177]
	global_load_lds_dwordx4 v[0:1], off
	v_lshl_add_u64 v[0:1], s[4:5], 0, v[172:173]
	s_add_i32 m0, s34, 0x1e000
	v_readlane_b32 s4, v253, 60
	global_load_lds_dwordx4 v[0:1], off
	v_readlane_b32 s6, v253, 62
	v_lshlrev_b32_e32 v1, 3, v190
	v_readlane_b32 s5, v253, 61
	v_readlane_b32 s7, v253, 63
	s_add_u32 s4, s6, 0x13400000
	v_and_b32_e32 v0, 16, v18
	v_and_b32_e32 v1, 0x80, v1
	s_movk_i32 s8, 0xb00
	s_addc_u32 s5, s7, 0
	v_or3_b32 v193, v0, v1, s39
	v_lshrrev_b32_e32 v1, 1, v13
	v_mul_lo_u32 v0, v12, s8
	s_mov_b32 s9, 0xb000
	v_bitop3_b32 v192, v16, s3, v17 bitop3:0xde
	s_cmpk_lt_u32 s2, 0x100
	v_mad_u64_u32 v[0:1], s[2:3], v1, s9, v[0:1]
	v_or_b32_e32 v0, v0, v14
	v_add_lshl_u32 v180, v0, v15, 1
	v_lshrrev_b32_e32 v1, 1, v8
	v_mul_lo_u32 v0, v9, s8
	s_waitcnt vmcnt(4)
	v_mad_u64_u32 v[0:1], s[2:3], v1, s9, v[0:1]
	v_or_b32_e32 v0, v0, v10
	s_cselect_b64 s[6:7], -1, 0
	v_or_b32_e32 v194, s39, v18
	v_mov_b32_e32 v181, v81
	v_add_lshl_u32 v184, v0, v11, 1
	v_mov_b32_e32 v185, v81
	s_mov_b32 s42, 0
	v_add_u32_e32 v195, 0, v19
	s_barrier
	s_branch .LBB0_142

; #define PG8_STAGE(bufoff, gbase, voff) do { _Pragma("unroll") for (int _i = 0; _i < 2; ++_i) \
;         __builtin_amdgcn_global_load_lds((const unsigned*)((const char*)(gbase) + (voff)[_i]), (PG8_LAS unsigned*)(lds + (bufoff) + ldsw + _i * 8192), 16, 0, 0); } while (0)
; #define PG8_LDA(dst, b, h) do { _Pragma("unroll") for (int m = 0; m < 4; ++m) _Pragma("unroll") for (int k = 0; k < 2; ++k) dst[m][k] = *(const PG8_LAS bf16x8*)(lds + PG8_SA(b, h) + aoff + m * 2048 + k * 1024); } while (0)
; #define PG8_LDB(dst, b, h) do { _Pragma("unroll") for (int n = 0; n < 2; ++n) _Pragma("unroll") for (int k = 0; k < 2; ++k) dst[n][k] = *(const PG8_LAS bf16x8*)(lds + PG8_SB(b, h) + boff + n * 2048 + k * 1024); } while (0)
; #define PG8_MMA(ai, bj, At, Bt) do { __builtin_amdgcn_s_setprio(1); _Pragma("unroll") for (int m = 0; m < 4; ++m) _Pragma("unroll") for (int n = 0; n < 2; ++n) _Pragma("unroll") for (int k = 0; k < 2; ++k) \
;         acc[ai][bj][m][n] = __builtin_amdgcn_mfma_f32_16x16x32_bf16(Bt[n][k], At[m][k], acc[ai][bj][m][n], 0, 0, 0); __builtin_amdgcn_s_setprio(0); } while (0)
; #define PG8_WAIT_V(n) asm volatile("s_waitcnt vmcnt(" #n ")" ::: "memory")
; #define PG8_WAIT_L(n) asm volatile("s_waitcnt lgkmcnt(" #n ")" ::: "memory")
; #define PG8_BAR __builtin_amdgcn_s_barrier()
; #define PG8_SCHED __builtin_amdgcn_sched_barrier(0)
; template <class Epi, class Sched, bool ALIGN_EPI = false>
; __device__ __forceinline__ void gemm_phase(PG8_LAS unsigned char* lds, const Gemm g, const Sched& S, const Epi& E, int tid_in) {
;     ...
;             PG8_LDB(B0, 0, 0); PG8_LDB(B1, 0, 1); PG8_SCHED; PG8_LDA(At, 0, 0); PG8_STAGE(PG8_SA(1, 1), a1 + hstepA, voffA);
;             PG8_WAIT_V(8); PG8_WAIT_L(0); PG8_BAR; PG8_MMA(0, 0, At, B0); PG8_MMA(0, 1, At, B1); PG8_BAR; PG8_SCHED;
;             PG8_LDA(At, 0, 1); PG8_STAGE(PG8_SB(0, 0), b2, voffB); PG8_STAGE(PG8_SB(0, 1), b2 + hstepB, voffB); PG8_STAGE(PG8_SA(0, 0), a2, voffA);
;             PG8_WAIT_V(8); PG8_WAIT_L(0); PG8_BAR; PG8_MMA(1, 0, At, B0); PG8_MMA(1, 1, At, B1); PG8_BAR; PG8_SCHED;
.LBB0_152:
	s_add_u32 s18, s14, s16
	s_addc_u32 s19, s15, s17
	s_add_u32 s18, s18, 0x100
	s_addc_u32 s19, s19, 0
	s_add_u32 s22, s49, s16
	s_addc_u32 s23, s50, s17
	s_cmpk_eq_i32 s16, 0x700
	s_cselect_b32 s21, s11, s19
	s_cselect_b32 s20, s10, s18
	s_cselect_b32 s19, s45, s23
	s_cselect_b32 s18, s46, s22
	s_add_i32 s22, 0, 0x10000
	v_add_u32_e32 v80, s22, v192
	s_add_i32 s52, 0, 0x14000
	ds_read_b128 v[132:135], v80
	ds_read_b128 v[136:139], v80 offset:1024
	ds_read_b128 v[140:143], v80 offset:2048
	ds_read_b128 v[144:147], v80 offset:3072
	v_add_u32_e32 v80, s52, v192
	ds_read_b128 v[148:151], v80
	ds_read_b128 v[152:155], v80 offset:1024
	ds_read_b128 v[156:159], v80 offset:2048
	ds_read_b128 v[160:163], v80 offset:3072
	v_lshl_add_u64 v[82:83], v[186:187], 0, s[16:17]
	s_add_i32 m0, s34, 0xc000
	ds_read_b128 v[164:167], v195
	ds_read_b128 v[168:171], v195 offset:1024
	ds_read_b128 v[196:199], v195 offset:2048
	ds_read_b128 v[200:203], v195 offset:3072
	ds_read_b128 v[204:207], v195 offset:4096
	ds_read_b128 v[208:211], v195 offset:5120
	ds_read_b128 v[212:215], v195 offset:6144
	ds_read_b128 v[216:219], v195 offset:7168
	v_lshl_add_u64 v[244:245], s[14:15], 0, v[178:179]
	v_lshl_add_u64 v[246:247], s[14:15], 0, v[174:175]
	v_lshl_add_u64 v[244:245], v[244:245], 0, s[16:17]
	v_lshl_add_u64 v[246:247], v[246:247], 0, s[16:17]
	v_lshl_add_u64 v[244:245], v[244:245], 0, s[96:97]
	s_mov_b32 m0, s40
	v_lshl_add_u64 v[246:247], v[246:247], 0, s[96:97]
	global_load_lds_dwordx4 v[244:245], off
	s_mov_b32 m0, s41
	s_nop 0
	global_load_lds_dwordx4 v[246:247], off
	s_add_i32 m0, s34, 0xc000
	s_nop 0
	global_load_lds_dwordx4 v[82:83], off
	v_lshl_add_u64 v[82:83], v[188:189], 0, s[16:17]
	s_add_i32 m0, s34, 0xe000
	s_nop 0
	global_load_lds_dwordx4 v[82:83], off
	s_waitcnt vmcnt(8)
	s_waitcnt lgkmcnt(0)
	v_mfma_f32_16x16x32_bf16 v[128:131], v[132:135], v[164:167], v[128:131]
	v_mfma_f32_16x16x32_bf16 v[124:127], v[140:143], v[164:167], v[124:127]
	s_barrier
	s_setprio 1
	s_waitcnt lgkmcnt(0)
	v_mfma_f32_16x16x32_bf16 v[112:115], v[132:135], v[196:199], v[112:115]
	v_mfma_f32_16x16x32_bf16 v[108:111], v[140:143], v[196:199], v[108:111]
	v_mfma_f32_16x16x32_bf16 v[96:99], v[132:135], v[204:207], v[96:99]
	v_mfma_f32_16x16x32_bf16 v[92:95], v[140:143], v[204:207], v[92:95]
	v_mfma_f32_16x16x32_bf16 v[76:79], v[132:135], v[212:215], v[76:79]
	v_mfma_f32_16x16x32_bf16 v[72:75], v[140:143], v[212:215], v[72:75]
	v_mfma_f32_16x16x32_bf16 v[128:131], v[136:139], v[168:171], v[128:131]
	v_mfma_f32_16x16x32_bf16 v[124:127], v[144:147], v[168:171], v[124:127]
	v_mfma_f32_16x16x32_bf16 v[112:115], v[136:139], v[200:203], v[112:115]
	v_mfma_f32_16x16x32_bf16 v[108:111], v[144:147], v[200:203], v[108:111]
	v_mfma_f32_16x16x32_bf16 v[96:99], v[136:139], v[208:211], v[96:99]
	v_mfma_f32_16x16x32_bf16 v[92:95], v[144:147], v[208:211], v[92:95]
	v_mfma_f32_16x16x32_bf16 v[76:79], v[136:139], v[216:219], v[76:79]
	v_mfma_f32_16x16x32_bf16 v[72:75], v[144:147], v[216:219], v[72:75]
	s_setprio 0
	s_setprio 1
	v_mfma_f32_16x16x32_bf16 v[120:123], v[148:151], v[164:167], v[120:123]
	v_mfma_f32_16x16x32_bf16 v[116:119], v[156:159], v[164:167], v[116:119]
	v_mfma_f32_16x16x32_bf16 v[104:107], v[148:151], v[196:199], v[104:107]
	v_mfma_f32_16x16x32_bf16 v[100:103], v[156:159], v[196:199], v[100:103]
	v_mfma_f32_16x16x32_bf16 v[88:91], v[148:151], v[204:207], v[88:91]
	v_mfma_f32_16x16x32_bf16 v[82:85], v[156:159], v[204:207], v[84:87]
	v_mfma_f32_16x16x32_bf16 v[68:71], v[148:151], v[212:215], v[68:71]
	v_mfma_f32_16x16x32_bf16 v[64:67], v[156:159], v[212:215], v[64:67]
	v_mfma_f32_16x16x32_bf16 v[120:123], v[152:155], v[168:171], v[120:123]
	v_mfma_f32_16x16x32_bf16 v[116:119], v[160:163], v[168:171], v[116:119]
	v_mfma_f32_16x16x32_bf16 v[104:107], v[152:155], v[200:203], v[104:107]
	v_mfma_f32_16x16x32_bf16 v[100:103], v[160:163], v[200:203], v[100:103]
	v_mfma_f32_16x16x32_bf16 v[88:91], v[152:155], v[208:211], v[88:91]
	v_mfma_f32_16x16x32_bf16 v[82:85], v[160:163], v[208:211], v[82:85]
	v_mfma_f32_16x16x32_bf16 v[68:71], v[152:155], v[216:219], v[68:71]
	v_mfma_f32_16x16x32_bf16 v[64:67], v[160:163], v[216:219], v[64:67]
	s_setprio 0
	s_barrier
	s_add_i32 s22, s22, s33
	v_lshl_add_u64 v[244:245], s[18:19], 0, v[176:177]
	s_mov_b32 m0, s22
	ds_read_b128 v[164:167], v195 offset:16384
	ds_read_b128 v[168:171], v195 offset:17408
	ds_read_b128 v[196:199], v195 offset:18432
	ds_read_b128 v[200:203], v195 offset:19456
	ds_read_b128 v[204:207], v195 offset:20480
	ds_read_b128 v[208:211], v195 offset:21504
	ds_read_b128 v[212:215], v195 offset:22528
	ds_read_b128 v[216:219], v195 offset:23552
	global_load_lds_dwordx4 v[244:245], off
	s_add_i32 m0, s22, 0x2000
	s_add_u32 s22, s18, 0x40000
	v_lshl_add_u64 v[246:247], s[18:19], 0, v[172:173]
	s_addc_u32 s23, s19, 0
	s_add_i32 s52, s52, s33
	global_load_lds_dwordx4 v[246:247], off
	v_lshl_add_u64 v[86:87], s[22:23], 0, v[176:177]
	s_mov_b32 m0, s52
	v_lshl_add_u64 v[248:249], s[20:21], 0, v[178:179]
	global_load_lds_dwordx4 v[86:87], off
	v_lshl_add_u64 v[86:87], s[22:23], 0, v[172:173]
	s_add_i32 m0, s52, 0x2000
	v_lshl_add_u64 v[228:229], s[20:21], 0, v[174:175]
	global_load_lds_dwordx4 v[86:87], off
	s_waitcnt vmcnt(6)
	s_waitcnt lgkmcnt(0)
	v_mfma_f32_16x16x32_bf16 v[60:63], v[132:135], v[164:167], v[60:63]
	v_mfma_f32_16x16x32_bf16 v[56:59], v[140:143], v[164:167], v[56:59]
	s_barrier
; #define PG8_STAGE(bufoff, gbase, voff) do { _Pragma("unroll") for (int _i = 0; _i < 2; ++_i) \
;         __builtin_amdgcn_global_load_lds((const unsigned*)((const char*)(gbase) + (voff)[_i]), (PG8_LAS unsigned*)(lds + (bufoff) + ldsw + _i * 8192), 16, 0, 0); } while (0)
; #define PG8_LDA(dst, b, h) do { _Pragma("unroll") for (int m = 0; m < 4; ++m) _Pragma("unroll") for (int k = 0; k < 2; ++k) dst[m][k] = *(const PG8_LAS bf16x8*)(lds + PG8_SA(b, h) + aoff + m * 2048 + k * 1024); } while (0)
; #define PG8_LDB(dst, b, h) do { _Pragma("unroll") for (int n = 0; n < 2; ++n) _Pragma("unroll") for (int k = 0; k < 2; ++k) dst[n][k] = *(const PG8_LAS bf16x8*)(lds + PG8_SB(b, h) + boff + n * 2048 + k * 1024); } while (0)
; #define PG8_MMA(ai, bj, At, Bt) do { __builtin_amdgcn_s_setprio(1); _Pragma("unroll") for (int m = 0; m < 4; ++m) _Pragma("unroll") for (int n = 0; n < 2; ++n) _Pragma("unroll") for (int k = 0; k < 2; ++k) \
;         acc[ai][bj][m][n] = __builtin_amdgcn_mfma_f32_16x16x32_bf16(Bt[n][k], At[m][k], acc[ai][bj][m][n], 0, 0, 0); __builtin_amdgcn_s_setprio(0); } while (0)
; #define PG8_WAIT_V(n) asm volatile("s_waitcnt vmcnt(" #n ")" ::: "memory")
; #define PG8_WAIT_L(n) asm volatile("s_waitcnt lgkmcnt(" #n ")" ::: "memory")
; #define PG8_BAR __builtin_amdgcn_s_barrier()
; #define PG8_SCHED __builtin_amdgcn_sched_barrier(0)
; template <class Epi, class Sched, bool ALIGN_EPI = false>
; __device__ __forceinline__ void gemm_phase(PG8_LAS unsigned char* lds, const Gemm g, const Sched& S, const Epi& E, int tid_in) {
;     ...
;             PG8_WAIT_V(8); PG8_WAIT_L(0); PG8_BAR; PG8_MMA(1, 0, At, B0); PG8_MMA(1, 1, At, B1); PG8_BAR; PG8_SCHED;
;             PG8_LDB(B0, 1, 0); PG8_LDB(B1, 1, 1); PG8_SCHED; PG8_LDA(At, 1, 0); PG8_STAGE(PG8_SA(0, 1), a2 + hstepA, voffA);
;             PG8_WAIT_V(8); PG8_WAIT_L(0); PG8_BAR; PG8_MMA(0, 0, At, B0); PG8_MMA(0, 1, At, B1); PG8_BAR; PG8_SCHED;
	s_setprio 1
	s_waitcnt lgkmcnt(0)
	v_mfma_f32_16x16x32_bf16 v[44:47], v[132:135], v[196:199], v[44:47]
	v_mfma_f32_16x16x32_bf16 v[40:43], v[140:143], v[196:199], v[40:43]
	v_mfma_f32_16x16x32_bf16 v[28:31], v[132:135], v[204:207], v[28:31]
	v_mfma_f32_16x16x32_bf16 v[24:27], v[140:143], v[204:207], v[24:27]
	v_mfma_f32_16x16x32_bf16 v[12:15], v[132:135], v[212:215], v[12:15]
	v_mfma_f32_16x16x32_bf16 v[8:11], v[140:143], v[212:215], v[8:11]
	v_mfma_f32_16x16x32_bf16 v[60:63], v[136:139], v[168:171], v[60:63]
	v_mfma_f32_16x16x32_bf16 v[56:59], v[144:147], v[168:171], v[56:59]
	v_mfma_f32_16x16x32_bf16 v[44:47], v[136:139], v[200:203], v[44:47]
	v_mfma_f32_16x16x32_bf16 v[40:43], v[144:147], v[200:203], v[40:43]
	v_mfma_f32_16x16x32_bf16 v[28:31], v[136:139], v[208:211], v[28:31]
	v_mfma_f32_16x16x32_bf16 v[24:27], v[144:147], v[208:211], v[24:27]
	v_mfma_f32_16x16x32_bf16 v[12:15], v[136:139], v[216:219], v[12:15]
	v_mfma_f32_16x16x32_bf16 v[8:11], v[144:147], v[216:219], v[8:11]
	s_setprio 0
	s_setprio 1
	v_mfma_f32_16x16x32_bf16 v[52:55], v[148:151], v[164:167], v[52:55]
	v_mfma_f32_16x16x32_bf16 v[48:51], v[156:159], v[164:167], v[48:51]
	v_mfma_f32_16x16x32_bf16 v[36:39], v[148:151], v[196:199], v[36:39]
	v_mfma_f32_16x16x32_bf16 v[32:35], v[156:159], v[196:199], v[32:35]
	v_mfma_f32_16x16x32_bf16 v[20:23], v[148:151], v[204:207], v[20:23]
	v_mfma_f32_16x16x32_bf16 v[16:19], v[156:159], v[204:207], v[16:19]
	v_mfma_f32_16x16x32_bf16 v[4:7], v[148:151], v[212:215], v[4:7]
	v_mfma_f32_16x16x32_bf16 v[0:3], v[156:159], v[212:215], v[0:3]
	v_mfma_f32_16x16x32_bf16 v[52:55], v[152:155], v[168:171], v[52:55]
	v_mfma_f32_16x16x32_bf16 v[48:51], v[160:163], v[168:171], v[48:51]
	v_mfma_f32_16x16x32_bf16 v[36:39], v[152:155], v[200:203], v[36:39]
	v_mfma_f32_16x16x32_bf16 v[32:35], v[160:163], v[200:203], v[32:35]
	v_mfma_f32_16x16x32_bf16 v[20:23], v[152:155], v[208:211], v[20:23]
	v_mfma_f32_16x16x32_bf16 v[16:19], v[160:163], v[208:211], v[16:19]
	v_mfma_f32_16x16x32_bf16 v[4:7], v[152:155], v[216:219], v[4:7]
	v_mfma_f32_16x16x32_bf16 v[0:3], v[160:163], v[216:219], v[0:3]
	s_setprio 0
	s_barrier
	s_add_i32 s22, 0, 0x18000
	v_add_u32_e32 v80, s22, v192
	s_add_i32 s23, 0, 0x1c000
	ds_read_b128 v[132:135], v80
	ds_read_b128 v[136:139], v80 offset:1024
	ds_read_b128 v[140:143], v80 offset:2048
	ds_read_b128 v[144:147], v80 offset:3072
	v_add_u32_e32 v80, s23, v192
	ds_read_b128 v[148:151], v80
	ds_read_b128 v[152:155], v80 offset:1024
	ds_read_b128 v[156:159], v80 offset:2048
	ds_read_b128 v[160:163], v80 offset:3072
	s_add_u32 s20, s20, 0xb0000
	s_addc_u32 s21, s21, 0
	s_mov_b32 m0, s34
	v_lshl_add_u64 v[86:87], s[20:21], 0, v[178:179]
	ds_read_b128 v[164:167], v195 offset:32768
	ds_read_b128 v[168:171], v195 offset:33792
	ds_read_b128 v[196:199], v195 offset:34816
	ds_read_b128 v[200:203], v195 offset:35840
	ds_read_b128 v[204:207], v195 offset:36864
	ds_read_b128 v[208:211], v195 offset:37888
	ds_read_b128 v[212:215], v195 offset:38912
	ds_read_b128 v[216:219], v195 offset:39936
	global_load_lds_dwordx4 v[248:249], off
	s_mov_b32 m0, s35
	s_nop 0
	global_load_lds_dwordx4 v[228:229], off
	s_mov_b32 m0, s36
	s_nop 0
	global_load_lds_dwordx4 v[86:87], off
	v_lshl_add_u64 v[86:87], s[20:21], 0, v[174:175]
	s_mov_b32 m0, s37
	s_nop 0
	global_load_lds_dwordx4 v[86:87], off
	s_waitcnt vmcnt(8)
	s_waitcnt lgkmcnt(0)
	v_mfma_f32_16x16x32_bf16 v[128:131], v[132:135], v[164:167], v[128:131]
	v_mfma_f32_16x16x32_bf16 v[124:127], v[140:143], v[164:167], v[124:127]
	s_barrier
; #define PG8_STAGE(bufoff, gbase, voff) do { _Pragma("unroll") for (int _i = 0; _i < 2; ++_i) \
;         __builtin_amdgcn_global_load_lds((const unsigned*)((const char*)(gbase) + (voff)[_i]), (PG8_LAS unsigned*)(lds + (bufoff) + ldsw + _i * 8192), 16, 0, 0); } while (0)
; #define PG8_LDA(dst, b, h) do { _Pragma("unroll") for (int m = 0; m < 4; ++m) _Pragma("unroll") for (int k = 0; k < 2; ++k) dst[m][k] = *(const PG8_LAS bf16x8*)(lds + PG8_SA(b, h) + aoff + m * 2048 + k * 1024); } while (0)
; #define PG8_MMA(ai, bj, At, Bt) do { __builtin_amdgcn_s_setprio(1); _Pragma("unroll") for (int m = 0; m < 4; ++m) _Pragma("unroll") for (int n = 0; n < 2; ++n) _Pragma("unroll") for (int k = 0; k < 2; ++k) \
;         acc[ai][bj][m][n] = __builtin_amdgcn_mfma_f32_16x16x32_bf16(Bt[n][k], At[m][k], acc[ai][bj][m][n], 0, 0, 0); __builtin_amdgcn_s_setprio(0); } while (0)
; #define PG8_WAIT_V(n) asm volatile("s_waitcnt vmcnt(" #n ")" ::: "memory")
; #define PG8_WAIT_L(n) asm volatile("s_waitcnt lgkmcnt(" #n ")" ::: "memory")
; #define PG8_BAR __builtin_amdgcn_s_barrier()
; #define PG8_SCHED __builtin_amdgcn_sched_barrier(0)
;     __device__ __forceinline__ unsigned char* ws() const { return *(const __attribute__((address_space(4))) ucptr_t*)(p + 264); }
;     __device__ __forceinline__ void mid(f32x4 (&acc)[2][2][4][2], const Unit& u, int t, int tid, int wr, int wc) const {
;         if (t == 6 || t == 12) { int tl = tid; asm volatile("" : "+v"(tl)); const int lane = tl & 63; merge_rescale(ws + EP_GT, t == 6 ? 0 : 1, acc, u, wr, wc, lane & 15, lane >> 4); }
; template <class Epi, class Sched, bool ALIGN_EPI = false>
; __device__ __forceinline__ void gemm_phase(PG8_LAS unsigned char* lds, const Gemm g, const Sched& S, const Epi& E, int tid_in) {
;     ...
;             PG8_WAIT_V(8); PG8_WAIT_L(0); PG8_BAR; PG8_MMA(0, 0, At, B0); PG8_MMA(0, 1, At, B1); PG8_BAR; PG8_SCHED;
;             PG8_LDA(At, 1, 1); PG8_STAGE(PG8_SB(1, 0), b3, voffB); PG8_STAGE(PG8_SB(1, 1), b3 + hstepB, voffB); PG8_STAGE(PG8_SA(1, 0), a3, voffA);
;             PG8_WAIT_V(8); PG8_WAIT_L(0); PG8_BAR; PG8_MMA(1, 0, At, B0); PG8_MMA(1, 1, At, B1); PG8_BAR; PG8_SCHED;
;         }
	s_setprio 1
	s_waitcnt lgkmcnt(0)
	v_mfma_f32_16x16x32_bf16 v[112:115], v[132:135], v[196:199], v[112:115]
	v_mfma_f32_16x16x32_bf16 v[108:111], v[140:143], v[196:199], v[108:111]
	v_mfma_f32_16x16x32_bf16 v[96:99], v[132:135], v[204:207], v[96:99]
	v_mfma_f32_16x16x32_bf16 v[92:95], v[140:143], v[204:207], v[92:95]
	v_mfma_f32_16x16x32_bf16 v[76:79], v[132:135], v[212:215], v[76:79]
	v_mfma_f32_16x16x32_bf16 v[72:75], v[140:143], v[212:215], v[72:75]
	v_mfma_f32_16x16x32_bf16 v[128:131], v[136:139], v[168:171], v[128:131]
	v_mfma_f32_16x16x32_bf16 v[124:127], v[144:147], v[168:171], v[124:127]
	v_mfma_f32_16x16x32_bf16 v[112:115], v[136:139], v[200:203], v[112:115]
	v_mfma_f32_16x16x32_bf16 v[108:111], v[144:147], v[200:203], v[108:111]
	v_mfma_f32_16x16x32_bf16 v[96:99], v[136:139], v[208:211], v[96:99]
	v_mfma_f32_16x16x32_bf16 v[92:95], v[144:147], v[208:211], v[92:95]
	v_mfma_f32_16x16x32_bf16 v[76:79], v[136:139], v[216:219], v[76:79]
	v_mfma_f32_16x16x32_bf16 v[72:75], v[144:147], v[216:219], v[72:75]
	s_setprio 0
	s_setprio 1
	v_mfma_f32_16x16x32_bf16 v[120:123], v[148:151], v[164:167], v[120:123]
	v_mfma_f32_16x16x32_bf16 v[116:119], v[156:159], v[164:167], v[116:119]
	v_mfma_f32_16x16x32_bf16 v[104:107], v[148:151], v[196:199], v[104:107]
	v_mfma_f32_16x16x32_bf16 v[100:103], v[156:159], v[196:199], v[100:103]
	v_mfma_f32_16x16x32_bf16 v[86:89], v[148:151], v[204:207], v[88:91]
	v_mfma_f32_16x16x32_bf16 v[82:85], v[156:159], v[204:207], v[82:85]
	v_mfma_f32_16x16x32_bf16 v[68:71], v[148:151], v[212:215], v[68:71]
	v_mfma_f32_16x16x32_bf16 v[64:67], v[156:159], v[212:215], v[64:67]
	v_mfma_f32_16x16x32_bf16 v[120:123], v[152:155], v[168:171], v[120:123]
	v_mfma_f32_16x16x32_bf16 v[116:119], v[160:163], v[168:171], v[116:119]
	v_mfma_f32_16x16x32_bf16 v[104:107], v[152:155], v[200:203], v[104:107]
	v_mfma_f32_16x16x32_bf16 v[100:103], v[160:163], v[200:203], v[100:103]
	v_mfma_f32_16x16x32_bf16 v[88:91], v[152:155], v[208:211], v[86:89]
	v_mfma_f32_16x16x32_bf16 v[84:87], v[160:163], v[208:211], v[82:85]
	v_mfma_f32_16x16x32_bf16 v[68:71], v[152:155], v[216:219], v[68:71]
	v_mfma_f32_16x16x32_bf16 v[64:67], v[160:163], v[216:219], v[64:67]
	s_setprio 0
	s_barrier
	s_add_i32 s20, s22, s33
	v_lshl_add_u64 v[82:83], v[244:245], 0, s[96:97]
	s_mov_b32 m0, s20
	ds_read_b128 v[164:167], v195 offset:49152
	ds_read_b128 v[168:171], v195 offset:50176
	ds_read_b128 v[196:199], v195 offset:51200
	ds_read_b128 v[200:203], v195 offset:52224
	ds_read_b128 v[204:207], v195 offset:53248
	ds_read_b128 v[208:211], v195 offset:54272
	ds_read_b128 v[212:215], v195 offset:55296
	ds_read_b128 v[216:219], v195 offset:56320
	global_load_lds_dwordx4 v[82:83], off
	s_add_i32 m0, s20, 0x2000
	s_add_u32 s18, s18, 0x40080
	v_lshl_add_u64 v[82:83], v[246:247], 0, s[96:97]
	s_addc_u32 s19, s19, 0
	s_add_i32 s20, s23, s33
	global_load_lds_dwordx4 v[82:83], off
	v_lshl_add_u64 v[82:83], s[18:19], 0, v[176:177]
	s_mov_b32 m0, s20
	s_nop 0
	global_load_lds_dwordx4 v[82:83], off
	v_lshl_add_u64 v[82:83], s[18:19], 0, v[172:173]
	s_add_i32 m0, s20, 0x2000
	s_nop 0
	global_load_lds_dwordx4 v[82:83], off
	s_waitcnt vmcnt(6)
	s_waitcnt lgkmcnt(0)
	v_mfma_f32_16x16x32_bf16 v[60:63], v[132:135], v[164:167], v[60:63]
	v_mfma_f32_16x16x32_bf16 v[56:59], v[140:143], v[164:167], v[56:59]
	s_barrier
	s_setprio 1
	s_waitcnt lgkmcnt(0)
	v_mfma_f32_16x16x32_bf16 v[44:47], v[132:135], v[196:199], v[44:47]
	v_mfma_f32_16x16x32_bf16 v[40:43], v[140:143], v[196:199], v[40:43]
	v_mfma_f32_16x16x32_bf16 v[28:31], v[132:135], v[204:207], v[28:31]
	v_mfma_f32_16x16x32_bf16 v[24:27], v[140:143], v[204:207], v[24:27]
	v_mfma_f32_16x16x32_bf16 v[12:15], v[132:135], v[212:215], v[12:15]
	v_mfma_f32_16x16x32_bf16 v[8:11], v[140:143], v[212:215], v[8:11]
	v_mfma_f32_16x16x32_bf16 v[60:63], v[136:139], v[168:171], v[60:63]
	v_mfma_f32_16x16x32_bf16 v[56:59], v[144:147], v[168:171], v[56:59]
	v_mfma_f32_16x16x32_bf16 v[44:47], v[136:139], v[200:203], v[44:47]
	v_mfma_f32_16x16x32_bf16 v[40:43], v[144:147], v[200:203], v[40:43]
	v_mfma_f32_16x16x32_bf16 v[28:31], v[136:139], v[208:211], v[28:31]
	v_mfma_f32_16x16x32_bf16 v[24:27], v[144:147], v[208:211], v[24:27]
	v_mfma_f32_16x16x32_bf16 v[12:15], v[136:139], v[216:219], v[12:15]
	v_mfma_f32_16x16x32_bf16 v[8:11], v[144:147], v[216:219], v[8:11]
	s_setprio 0
	s_setprio 1
	v_mfma_f32_16x16x32_bf16 v[52:55], v[148:151], v[164:167], v[52:55]
	v_mfma_f32_16x16x32_bf16 v[48:51], v[156:159], v[164:167], v[48:51]
	v_mfma_f32_16x16x32_bf16 v[36:39], v[148:151], v[196:199], v[36:39]
	v_mfma_f32_16x16x32_bf16 v[32:35], v[156:159], v[196:199], v[32:35]
	v_mfma_f32_16x16x32_bf16 v[20:23], v[148:151], v[204:207], v[20:23]
	v_mfma_f32_16x16x32_bf16 v[16:19], v[156:159], v[204:207], v[16:19]
	v_mfma_f32_16x16x32_bf16 v[4:7], v[148:151], v[212:215], v[4:7]
	v_mfma_f32_16x16x32_bf16 v[0:3], v[156:159], v[212:215], v[0:3]
	v_mfma_f32_16x16x32_bf16 v[52:55], v[152:155], v[168:171], v[52:55]
	v_mfma_f32_16x16x32_bf16 v[48:51], v[160:163], v[168:171], v[48:51]
	v_mfma_f32_16x16x32_bf16 v[36:39], v[152:155], v[200:203], v[36:39]
	v_mfma_f32_16x16x32_bf16 v[32:35], v[160:163], v[200:203], v[32:35]
	v_mfma_f32_16x16x32_bf16 v[20:23], v[152:155], v[208:211], v[20:23]
	v_mfma_f32_16x16x32_bf16 v[16:19], v[160:163], v[208:211], v[16:19]
	v_mfma_f32_16x16x32_bf16 v[4:7], v[152:155], v[216:219], v[4:7]
	v_mfma_f32_16x16x32_bf16 v[0:3], v[160:163], v[216:219], v[0:3]
	s_setprio 0
	s_barrier
	s_add_i32 s18, s51, 2
	s_add_u32 s16, s16, 0x100
	s_addc_u32 s17, s17, 0
	s_cmp_gt_u32 s51, 13
	s_cbranch_scc1 .LBB0_154
	s_mov_b32 s51, s18
	s_cmp_lt_i32 s51, 12
	s_cbranch_scc1 .LBB0_148
	s_branch .LBB0_147
